# attention: static s_setprio 1 for the map-0 waves (waves 0-3) during the tile loop, reset to 0 after each unit
# speedup vs baseline: 1.0040x; 1.0009x over previous
; #define MFMA32(a, b, c) __builtin_amdgcn_mfma_f32_32x32x16_bf16((a), (b), (c), 0, 0, 0)
; #define AT_NOP() asm volatile("s_nop 7\n\ts_nop 7" ::: "memory")
; #define AT_RD4(d0, d1, d2, d3, addr, o0, o1, o2, o3) do { DSR(d0, addr, o0); DSR(d1, addr, o1); DSR(d2, addr, o2); DSR(d3, addr, o3); } while (0)
; #define AT_WAIT8(a0, a1, a2, a3, a4, a5, a6, a7) asm volatile("s_waitcnt lgkmcnt(0)" : "+v"(a0), "+v"(a1), "+v"(a2), "+v"(a3), "+v"(a4), "+v"(a5), "+v"(a6), "+v"(a7) :: "memory")
; #define AT_PVRD(addr) do { AT_RDG(vf[0], vf[1], vf[2], vf[3], addr, 0); AT_RDG(vf[4], vf[5], vf[6], vf[7], addr, 1); } while (0)
; __device__ __forceinline__ void attn_phase(KA a, lds8* lds, int tid, int lane, int wave) {
;     ...
;             AT_RD4(kf[0], kf[1], kf[2], kf[3], kaddr0 + bcur, 0, 32, 64, 96); AT_RD4(vf[0], vf[1], vf[2], vf[3], kaddr0 + bcur, 4608, 4640, 4672, 4704);
;             AT_WAIT8(kf[0], kf[1], kf[2], kf[3], vf[0], vf[1], vf[2], vf[3]);
;             f32x16 s0, s1;
; #pragma unroll
;             for (int ks = 0; ks < 4; ++ks) { s0 = MFMA32(kf[ks], qf[ks], ks == 0 ? negm : s0); s1 = MFMA32(vf[ks], qf[ks], ks == 0 ? negm : s1); }
;             if (map == 0) { AT_NOP(); AT_PVRD(vaddr0 + bcur); }
.Lat_qk:
	v_cndmask_b32_e64 v176, 0, 1, s[20:21]
	s_waitcnt lgkmcnt(0)
	v_cmp_ne_u32_e64 s[12:13], 1, v176
	v_mfma_f32_32x32x16_bf16 v[96:111], v[112:115], v[128:131], v[64:79]
	s_andn2_b64 vcc, exec, s[20:21]
	v_add_u32_e32 v176, s18, v232
	v_mfma_f32_32x32x16_bf16 v[80:95], v[116:119], v[128:131], v[64:79]
	v_mfma_f32_32x32x16_bf16 v[96:111], v[220:223], v[132:135], v[96:111]
	v_mfma_f32_32x32x16_bf16 v[80:95], v[120:123], v[132:135], v[80:95]
	v_mfma_f32_32x32x16_bf16 v[96:111], v[224:227], v[136:139], v[96:111]
	v_mfma_f32_32x32x16_bf16 v[80:95], v[168:171], v[136:139], v[80:95]
	v_mfma_f32_32x32x16_bf16 v[96:111], v[228:231], v[140:143], v[96:111]
	v_mfma_f32_32x32x16_bf16 v[80:95], v[172:175], v[140:143], v[80:95]
	s_cbranch_vccnz .LBB0_1310
	s_setprio 1
	ds_read_b128 v[160:163], v176 offset:0
	ds_read_b128 v[164:167], v176 offset:0x1200
	ds_read_b128 v[168:171], v176 offset:0x2400
	ds_read_b128 v[172:175], v176 offset:0x3600
	ds_read_b128 v[112:115], v176 offset:32
	ds_read_b128 v[116:119], v176 offset:0x1220
	ds_read_b128 v[120:123], v176 offset:0x2420
	ds_read_b128 v[124:127], v176 offset:0x3620

; #define LAS __attribute__((address_space(3)))
; #define lane (pg8::pg8_lane_id())
; __device__ __forceinline__ void attn_phase(KA a, lds8* lds, int tid, int lane, int wave) {
;     ...
;         const float lsum = (lsA + lsB) + (lsC + lsD); const float ltot = lsum + __shfl_xor(lsum, 32); const float inv = 1.0f / ltot;
;         __syncthreads();
;         LAS float* ex = (LAS float*)lds;
;         if (map == 1) {
; #pragma unroll
;             for (int db = 0; db < 4; ++db)
; #pragma unroll
;                 for (int r = 0; r < 16; ++r) ex[(qg * 64 + db * 16 + r) * 64 + lane] = O[db][r] * inv;
;         }
.LBB0_1320:
	s_setprio 0
	v_add_f32_e32 v64, v211, v210
	v_add_f32_e32 v65, v209, v208
	v_add_f32_e32 v64, v64, v65
	ds_bpermute_b32 v65, v108, v64
	s_waitcnt lgkmcnt(0)
	s_barrier
	v_add_f32_e32 v64, v64, v65
	v_div_scale_f32 v65, s[8:9], v64, v64, 1.0
	v_rcp_f32_e32 v66, v65
	v_div_scale_f32 v67, vcc, 1.0, v64, 1.0
	v_fma_f32 v68, -v65, v66, 1.0
	v_fmac_f32_e32 v66, v68, v66
	v_mul_f32_e32 v68, v67, v66
	v_fma_f32 v69, -v65, v68, v67
	v_fmac_f32_e32 v68, v69, v66
	v_fma_f32 v65, -v65, v68, v67
	v_div_fmas_f32 v65, v65, v66, v68
	v_div_fixup_f32 v64, v65, v64, 1.0
	s_and_b64 vcc, exec, s[4:5]
	s_cbranch_vccnz .LBB0_1322
	v_mul_f32_e32 v65, v48, v64
	v_mul_f32_e32 v66, v49, v64
	ds_write2st64_b32 v242, v65, v66 offset1:1
	v_mul_f32_e32 v65, v50, v64
	v_mul_f32_e32 v66, v51, v64
	ds_write2st64_b32 v242, v65, v66 offset0:2 offset1:3
	v_mul_f32_e32 v65, v52, v64
	v_mul_f32_e32 v66, v53, v64
	ds_write2st64_b32 v242, v65, v66 offset0:4 offset1:5
	v_mul_f32_e32 v65, v54, v64
	v_mul_f32_e32 v66, v55, v64
	ds_write2st64_b32 v242, v65, v66 offset0:6 offset1:7
	v_mul_f32_e32 v65, v56, v64
	v_mul_f32_e32 v66, v57, v64
	ds_write2st64_b32 v242, v65, v66 offset0:8 offset1:9
	v_mul_f32_e32 v65, v58, v64
	v_mul_f32_e32 v66, v59, v64
	ds_write2st64_b32 v242, v65, v66 offset0:10 offset1:11
	v_mul_f32_e32 v65, v60, v64
	v_mul_f32_e32 v66, v61, v64
	ds_write2st64_b32 v242, v65, v66 offset0:12 offset1:13
	v_mul_f32_e32 v65, v62, v64
	v_mul_f32_e32 v66, v63, v64
	ds_write2st64_b32 v242, v65, v66 offset0:14 offset1:15
	v_mul_f32_e32 v65, v32, v64
	v_mul_f32_e32 v66, v33, v64
	ds_write2st64_b32 v242, v65, v66 offset0:16 offset1:17
	v_mul_f32_e32 v65, v34, v64
	v_mul_f32_e32 v66, v35, v64
	ds_write2st64_b32 v242, v65, v66 offset0:18 offset1:19
	v_mul_f32_e32 v65, v36, v64
	v_mul_f32_e32 v66, v37, v64
	ds_write2st64_b32 v242, v65, v66 offset0:20 offset1:21
	v_mul_f32_e32 v65, v38, v64
	v_mul_f32_e32 v66, v39, v64
	ds_write2st64_b32 v242, v65, v66 offset0:22 offset1:23
	v_mul_f32_e32 v65, v40, v64
	v_mul_f32_e32 v66, v41, v64
	ds_write2st64_b32 v242, v65, v66 offset0:24 offset1:25
	v_mul_f32_e32 v65, v42, v64
	v_mul_f32_e32 v66, v43, v64
	ds_write2st64_b32 v242, v65, v66 offset0:26 offset1:27
	v_mul_f32_e32 v65, v44, v64
	v_mul_f32_e32 v66, v45, v64
	ds_write2st64_b32 v242, v65, v66 offset0:28 offset1:29
	v_mul_f32_e32 v65, v46, v64
	v_mul_f32_e32 v66, v47, v64
	ds_write2st64_b32 v242, v65, v66 offset0:30 offset1:31
	v_mul_f32_e32 v65, v16, v64
	v_mul_f32_e32 v66, v17, v64
	ds_write2st64_b32 v242, v65, v66 offset0:32 offset1:33
	v_mul_f32_e32 v65, v18, v64
	v_mul_f32_e32 v66, v19, v64
	ds_write2st64_b32 v242, v65, v66 offset0:34 offset1:35
	v_mul_f32_e32 v65, v20, v64
	v_mul_f32_e32 v66, v21, v64
	ds_write2st64_b32 v242, v65, v66 offset0:36 offset1:37
	v_mul_f32_e32 v65, v22, v64
	v_mul_f32_e32 v66, v23, v64
	ds_write2st64_b32 v242, v65, v66 offset0:38 offset1:39
	v_mul_f32_e32 v65, v24, v64
	v_mul_f32_e32 v66, v25, v64
	ds_write2st64_b32 v242, v65, v66 offset0:40 offset1:41
	v_mul_f32_e32 v65, v26, v64
	v_mul_f32_e32 v66, v27, v64
	ds_write2st64_b32 v242, v65, v66 offset0:42 offset1:43
	v_mul_f32_e32 v65, v28, v64
	v_mul_f32_e32 v66, v29, v64
	ds_write2st64_b32 v242, v65, v66 offset0:44 offset1:45
	v_mul_f32_e32 v65, v30, v64
	v_mul_f32_e32 v66, v31, v64
	ds_write2st64_b32 v242, v65, v66 offset0:46 offset1:47
	v_mul_f32_e32 v65, v0, v64
	v_mul_f32_e32 v66, v1, v64
	ds_write2st64_b32 v242, v65, v66 offset0:48 offset1:49
	v_mul_f32_e32 v65, v2, v64
	v_mul_f32_e32 v66, v3, v64
	ds_write2st64_b32 v242, v65, v66 offset0:50 offset1:51
	v_mul_f32_e32 v65, v4, v64
	v_mul_f32_e32 v66, v5, v64
	ds_write2st64_b32 v242, v65, v66 offset0:52 offset1:53
	v_mul_f32_e32 v65, v6, v64
	v_mul_f32_e32 v66, v7, v64
	ds_write2st64_b32 v242, v65, v66 offset0:54 offset1:55
	v_mul_f32_e32 v65, v8, v64
	v_mul_f32_e32 v66, v9, v64
	ds_write2st64_b32 v242, v65, v66 offset0:56 offset1:57
	v_mul_f32_e32 v65, v10, v64
	v_mul_f32_e32 v66, v11, v64
	ds_write2st64_b32 v242, v65, v66 offset0:58 offset1:59
	v_mul_f32_e32 v65, v12, v64
	v_mul_f32_e32 v66, v13, v64
	ds_write2st64_b32 v242, v65, v66 offset0:60 offset1:61
	v_mul_f32_e32 v65, v14, v64
	v_mul_f32_e32 v66, v15, v64
	ds_write2st64_b32 v242, v65, v66 offset0:62 offset1:63
